# DeltaNet scan: deeper LDS fragment prefetch, scalar f32 ops instead of packed beside MFMAs, qk-helper load addressing hoisted, agent-scope coalesced atomics
# speedup vs baseline: 1.0107x; 1.0107x over previous
; __device__ __forceinline__ int opaque_tid() { int t = threadIdx.x; asm volatile("" : "+v"(t)); return t; }
; #define LAS __attribute__((address_space(3)))
; #define BAR_LDS() do { asm volatile("s_waitcnt lgkmcnt(0)" ::: "memory"); __builtin_amdgcn_s_barrier(); asm volatile("" ::: "memory"); } while (0)
; __device__ __forceinline__ bf16x8 frag_tr(const LAS bf16_t* img, int LD, int m0, int ks, int lane) {
;     const int i16 = lane & 15, q = i16 >> 2, p = i16 & 3, blk = (lane >> 4) & 1, h = lane >> 5;
;     const LAS bf16_t* a = img + (16 * ks + 4 * h + q) * LD + m0 + 16 * blk + 4 * p;
;     const s16x4 lo = tr4(a), hi = tr4(a + 8 * LD);
;     return __builtin_shufflevector(lo, hi, 0, 1, 2, 3, 4, 5, 6, 7);
; }
; template <int VAR> __device__ __forceinline__ void dn_scan3(LAS unsigned char* lds, const bf16_t* P, const float* AB, const bf16_t* TP, bf16_t* OB) {
;     ...
;             f32x16 S[4];
; #pragma unroll
;             for (int kt = 0; kt < 4; ++kt)
; #pragma unroll
;                 for (int x = 0; x < 16; ++x) S[kt][x] = 0.f;
;             BAR_LDS();
;             for (int step = 0; step < 260; ++step) {
;                 const int lane = opaque_tid() & 63, r = lane & 31, h = lane >> 5;
;                 LAS unsigned char* base = lds + (step & 1) * DN_DIR;
;                 LAS bf16_t* Kb = (LAS bf16_t*)(base + DN_KB); LAS bf16_t* Qb = (LAS bf16_t*)(base + DN_QB); LAS bf16_t* Vb = (LAS bf16_t*)(base + DN_VB);
;                 LAS bf16_t* Tb = (LAS bf16_t*)(base + DN_TB); LAS bf16_t* Ab = (LAS bf16_t*)(base + DN_AB);
;                 LAS float* sc_beta = (LAS float*)(base + DN_SC); LAS float* sc_eg = sc_beta + 128; LAS float* sc_tail = sc_beta + 192; LAS float* sc_dl = sc_beta + 256;
;                 int rb; bool f_; dn_step_rb(step, dir, b, rb, f_);
;                 if (VAR != 2) {
;                 f32x16 KS[2], QS[2];
; #pragma unroll
;                 for (int mt = 0; mt < 2; ++mt)
; #pragma unroll
;                     for (int x = 0; x < 16; ++x) { KS[mt][x] = 0.f; QS[mt][x] = 0.f; }
; #pragma unroll
;                 for (int ks = 0; ks < 8; ++ks) {
;                     const bf16x8 sp = pack_step(S[ks >> 1], ks & 1);
; #pragma unroll
;                     for (int mt = 0; mt < 2; ++mt) { KS[mt] = MFMA32(frag_perm(Kb, 136, 32 * mt + r, ks, h), sp, KS[mt]); QS[mt] = MFMA32(frag_perm(Qb, 136, 32 * mt + r, ks, h), sp, QS[mt]); }
.LBB0_375:
	s_mov_b64 s[40:41], -1
	s_and_b64 vcc, exec, s[0:1]
	s_waitcnt lgkmcnt(0)
	s_barrier
	s_cbranch_vccz .LBB0_379
	s_waitcnt lgkmcnt(0)
	s_barrier
	v_mov_b32_e32 v2, 0
	s_mov_b32 s40, 0
	v_mov_b32_e32 v3, v2
	v_mov_b32_e32 v4, v2
	v_mov_b32_e32 v5, v2
	v_mov_b32_e32 v6, v2
	v_mov_b32_e32 v7, v2
	v_mov_b32_e32 v8, v2
	v_mov_b32_e32 v9, v2
	v_mov_b32_e32 v10, v2
	v_mov_b32_e32 v11, v2
	v_mov_b32_e32 v12, v2
	v_mov_b32_e32 v13, v2
	v_mov_b32_e32 v14, v2
	v_mov_b32_e32 v15, v2
	v_mov_b32_e32 v16, v2
	v_mov_b32_e32 v17, v2
	v_mov_b32_e32 v18, v2
	v_mov_b32_e32 v19, v2
	v_mov_b32_e32 v20, v2
	v_mov_b32_e32 v21, v2
	v_mov_b32_e32 v22, v2
	v_mov_b32_e32 v23, v2
	v_mov_b32_e32 v24, v2
	v_mov_b32_e32 v25, v2
	v_mov_b32_e32 v26, v2
	v_mov_b32_e32 v27, v2
	v_mov_b32_e32 v28, v2
	v_mov_b32_e32 v29, v2
	v_mov_b32_e32 v30, v2
	v_mov_b32_e32 v31, v2
	v_mov_b32_e32 v32, v2
	v_mov_b32_e32 v33, v2
	v_mov_b32_e32 v34, v2
	v_mov_b32_e32 v35, v2
	v_mov_b32_e32 v36, v2
	v_mov_b32_e32 v37, v2
	v_mov_b32_e32 v38, v2
	v_mov_b32_e32 v39, v2
	v_mov_b32_e32 v40, v2
	v_mov_b32_e32 v41, v2
	v_mov_b32_e32 v42, v2
	v_mov_b32_e32 v43, v2
	v_mov_b32_e32 v44, v2
	v_mov_b32_e32 v45, v2
	v_mov_b32_e32 v46, v2
	v_mov_b32_e32 v47, v2
	v_mov_b32_e32 v48, v2
	v_mov_b32_e32 v49, v2
	v_mov_b32_e32 v50, v2
	v_mov_b32_e32 v51, v2
	v_mov_b32_e32 v52, v2
	v_mov_b32_e32 v53, v2
	v_mov_b32_e32 v54, v2
	v_mov_b32_e32 v55, v2
	v_mov_b32_e32 v56, v2
	v_mov_b32_e32 v57, v2
	v_mov_b32_e32 v58, v2
	v_mov_b32_e32 v59, v2
	v_mov_b32_e32 v60, v2
	v_mov_b32_e32 v61, v2
	v_mov_b32_e32 v62, v2
	v_mov_b32_e32 v63, v2
	v_mov_b32_e32 v64, v2
	v_mov_b32_e32 v65, v2
	v_and_b32_e32 v212, 31, v188
	v_bfe_u32 v213, v188, 5, 1
	v_mul_u32_u24_e32 v214, 0x110, v212
	v_lshl_add_u32 v207, v213, 4, v214
	v_mul_u32_u24_e32 v214, 0x90, v212
	v_lshl_add_u32 v210, v213, 4, v214
	v_lshlrev_b32_e32 v214, 1, v212
	v_lshl_add_u32 v214, v213, 10, v214
	v_add_u32_e32 v208, s18, v214
	v_lshlrev_b32_e32 v214, 4, v213
	v_add_u32_e32 v209, 0x11000, v214
	v_bfe_u32 v214, v188, 2, 2
	v_and_b32_e32 v215, 3, v188
	v_lshlrev_b32_e32 v215, 3, v215
	v_bfe_u32 v216, v188, 4, 1
	v_lshl_add_u32 v215, v216, 5, v215
	v_lshlrev_b32_e32 v216, 3, v214
	v_lshl_add_u32 v216, v213, 2, v216
	v_and_b32_e32 v217, 3, v214
	v_add_u32_e32 v217, v217, v216
	v_mul_u32_u24_e32 v217, 0x110, v217
	v_add_u32_e32 v211, v217, v215
	v_add_u32_e32 v217, 1, v214
	v_and_b32_e32 v217, 3, v217
	v_add_u32_e32 v217, v217, v216
	v_mul_u32_u24_e32 v217, 0x110, v217
	v_add_u32_e32 v201, v217, v215
	v_add_u32_e32 v217, 2, v214
	v_and_b32_e32 v217, 3, v217
	v_add_u32_e32 v217, v217, v216
	v_mul_u32_u24_e32 v217, 0x110, v217
	v_add_u32_e32 v180, v217, v215
	v_add_u32_e32 v217, 3, v214
	v_and_b32_e32 v217, 3, v217
	v_add_u32_e32 v217, v217, v216
	v_mul_u32_u24_e32 v217, 0x110, v217
	v_add_u32_e32 v217, v217, v215
	v_lshl_or_b32 v180, v217, 16, v180
	s_and_b32 s57, s54, 1
	s_lshr_b32 s45, s54, 5
	s_lshl_b32 s55, s45, 2
	s_addk_i32 s55, 0x200
	s_lshl_b32 s56, s45, 8
	s_bfe_u32 s48, s54, 0x40001
	s_lshl_b32 s48, s48, 8
	s_add_i32 s48, s48, s18
	s_add_u32 s58, s8, s48
	s_addc_u32 s59, s9, 0
	s_mul_i32 s49, s57, 63
	s_mov_b32 s60, 0
	s_lshl_b32 s61, s57, 15
	s_sub_i32 s61, 0x4000, s61
	s_lshl_b32 s62, s61, 1
	v_and_b32_e32 v212, 63, v188
	v_lshrrev_b32_e32 v213, 4, v212
	v_and_b32_e32 v214, 15, v212
	v_lshlrev_b32_e32 v214, 2, v214
	v_lshl_add_u32 v0, v213, 8, v214
	v_add_u32_e32 v0, s18, v0
	v_xor_b32_e32 v215, s49, v213
	v_lshl_add_u32 v194, v215, 12, v214
.LBB0_377:
	s_bitcmp1_b32 s40, 0
	s_cselect_b32 s41, 0x11600, 0
	v_add_u32_e32 v212, s41, v207
	v_add_u32_e32 v214, s41, v209
	v_add_u32_e32 v213, s41, v208
	v_add_u32_e32 v215, s41, v210
	s_add_i32 s42, s41, 0x11400
	v_mov_b32_e32 v217, s42
	v_add_u32_e32 v179, s41, v0
	s_add_i32 s44, s40, -4
	s_cmp_lt_u32 s40, 4
	s_cselect_b32 s44, s40, s44
	s_cselect_b32 s45, 3, 0xff
	s_cselect_b32 s48, s55, s56
	s_sub_i32 s45, s45, s44
	s_cmp_eq_u32 s57, 0
	s_cselect_b32 s44, s44, s45
	s_add_i32 s44, s44, s48
	s_lshl_b32 s44, s44, 18
	s_add_u32 s42, s58, s44
	s_addc_u32 s43, s59, 0
	ds_read_b128 v[138:141], v212 offset:0
	ds_read_b128 v[142:145], v212 offset:32
	ds_read_b128 v[146:149], v212 offset:64
	ds_read_b128 v[150:153], v212 offset:96
	ds_read_b128 v[154:157], v212 offset:128
	ds_read_b128 v[158:161], v212 offset:160
	v_cvt_pk_bf16_f32 v218, v50, v51
	v_cvt_pk_bf16_f32 v220, v54, v55
	v_cvt_pk_bf16_f32 v219, v52, v53
	v_cvt_pk_bf16_f32 v221, v56, v57
	v_cvt_pk_bf16_f32 v222, v58, v59
	v_cvt_pk_bf16_f32 v224, v62, v63
	v_cvt_pk_bf16_f32 v223, v60, v61
	v_cvt_pk_bf16_f32 v225, v64, v65
	v_permlane32_swap_b32_e32 v218, v220
	v_permlane32_swap_b32_e32 v219, v221
	v_permlane32_swap_b32_e32 v222, v224
	v_permlane32_swap_b32_e32 v223, v225
	ds_read_b128 v[162:165], v212 offset:192
	ds_read_b128 v[166:169], v212 offset:224
	s_waitcnt lgkmcnt(7)
	v_mfma_f32_32x32x16_bf16 v[66:81], v[138:141], v[218:221], 0
	v_cvt_pk_bf16_f32 v226, v34, v35
	v_cvt_pk_bf16_f32 v228, v38, v39
	v_cvt_pk_bf16_f32 v227, v36, v37
	v_cvt_pk_bf16_f32 v229, v40, v41
	v_permlane32_swap_b32_e32 v226, v228
	ds_read_b128 v[138:141], v212 offset:8704
	v_permlane32_swap_b32_e32 v227, v229
	ds_read_b128 v[170:173], v212 offset:8736
	s_waitcnt lgkmcnt(8)
	v_mfma_f32_32x32x16_bf16 v[66:81], v[142:145], v[222:225], v[66:81]
	v_cvt_pk_bf16_f32 v230, v42, v43
	v_cvt_pk_bf16_f32 v232, v46, v47
	v_cvt_pk_bf16_f32 v231, v44, v45
	v_cvt_pk_bf16_f32 v233, v48, v49
	v_permlane32_swap_b32_e32 v230, v232
	ds_read_b128 v[142:145], v212 offset:8768
	v_permlane32_swap_b32_e32 v231, v233
	s_waitcnt lgkmcnt(8)
; #define LAS __attribute__((address_space(3)))
; #define MFMA32(a, b, c) __builtin_amdgcn_mfma_f32_32x32x16_bf16((a), (b), (c), 0, 0, 0)
; template <int VAR> __device__ __forceinline__ void dn_scan3(LAS unsigned char* lds, const bf16_t* P, const float* AB, const bf16_t* TP, bf16_t* OB) {
;     ...
;                 for (int ks = 0; ks < 8; ++ks) {
;                     const bf16x8 sp = pack_step(S[ks >> 1], ks & 1);
; #pragma unroll
;                     for (int mt = 0; mt < 2; ++mt) { KS[mt] = MFMA32(frag_perm(Kb, 136, 32 * mt + r, ks, h), sp, KS[mt]); QS[mt] = MFMA32(frag_perm(Qb, 136, 32 * mt + r, ks, h), sp, QS[mt]); }
;                 }
;                 __builtin_amdgcn_iglp_opt(0);
; #pragma unroll
;                 for (int mt = 0; mt < 2; ++mt)
; #pragma unroll
;                     for (int g4 = 0; g4 < 4; ++g4) { const int i0 = 32 * mt + 8 * g4 + 4 * h;
;                         const f32x4 bv = *(const LAS f32x4*)(sc_beta + i0), ev = *(const LAS f32x4*)(sc_eg + i0);
; #pragma unroll
;                         for (int e = 0; e < 4; ++e) { const int x = 4 * g4 + e; KS[mt][x] = bv[e] * (bf2f(Vb[(i0 + e) * 128 + 32 * w + r]) - ev[e] * KS[mt][x]); } }
;                 bf16x8 Xp[4];
; #pragma unroll
;                 for (int ks = 0; ks < 4; ++ks) Xp[ks] = pack_step(KS[ks >> 1], ks & 1);
	v_mfma_f32_32x32x16_bf16 v[66:81], v[146:149], v[226:229], v[66:81]
	v_cvt_pk_bf16_f32 v234, v18, v19
	v_cvt_pk_bf16_f32 v236, v22, v23
	v_cvt_pk_bf16_f32 v235, v20, v21
	v_cvt_pk_bf16_f32 v237, v24, v25
	v_permlane32_swap_b32_e32 v234, v236
	ds_read_b128 v[146:149], v212 offset:8800
	v_permlane32_swap_b32_e32 v235, v237
	s_waitcnt lgkmcnt(8)
	v_mfma_f32_32x32x16_bf16 v[66:81], v[150:153], v[230:233], v[66:81]
	v_cvt_pk_bf16_f32 v238, v26, v27
	v_cvt_pk_bf16_f32 v240, v30, v31
	v_cvt_pk_bf16_f32 v239, v28, v29
	v_cvt_pk_bf16_f32 v241, v32, v33
	v_permlane32_swap_b32_e32 v238, v240
	ds_read_b128 v[150:153], v212 offset:8832
	v_permlane32_swap_b32_e32 v239, v241
	s_waitcnt lgkmcnt(8)
	v_mfma_f32_32x32x16_bf16 v[66:81], v[154:157], v[234:237], v[66:81]
	v_cvt_pk_bf16_f32 v242, v2, v3
	v_cvt_pk_bf16_f32 v244, v6, v7
	v_cvt_pk_bf16_f32 v243, v4, v5
	v_cvt_pk_bf16_f32 v245, v8, v9
	v_permlane32_swap_b32_e32 v242, v244
	ds_read_b128 v[154:157], v212 offset:8864
	v_permlane32_swap_b32_e32 v243, v245
	s_waitcnt lgkmcnt(8)
	v_mfma_f32_32x32x16_bf16 v[66:81], v[158:161], v[238:241], v[66:81]
	v_cvt_pk_bf16_f32 v246, v10, v11
	v_cvt_pk_bf16_f32 v248, v14, v15
	v_cvt_pk_bf16_f32 v247, v12, v13
	v_cvt_pk_bf16_f32 v249, v16, v17
	v_permlane32_swap_b32_e32 v246, v248
	ds_read_b128 v[158:161], v212 offset:8896
	v_permlane32_swap_b32_e32 v247, v249
	ds_read_u16 v114, v213 offset:34816
	ds_read_u16 v115, v213 offset:35072
	ds_read_u16 v116, v213 offset:35328
	ds_read_u16 v117, v213 offset:35584
	ds_read_b128 v[118:121], v214 offset:0
	ds_read_b128 v[122:125], v214 offset:512
	s_waitcnt lgkmcnt(14)
	v_mfma_f32_32x32x16_bf16 v[66:81], v[162:165], v[242:245], v[66:81]
	ds_read_u16 v126, v213 offset:36864
	ds_read_u16 v127, v213 offset:37120
	ds_read_u16 v128, v213 offset:37376
	ds_read_u16 v129, v213 offset:37632
	ds_read_b128 v[130:133], v214 offset:32
	ds_read_b128 v[134:137], v214 offset:544
	ds_read_b128 v[162:165], v212 offset:8928
	v_mfma_f32_32x32x16_bf16 v[66:81], v[166:169], v[246:249], v[66:81]
	ds_read_b128 v[166:169], v212 offset:17408
	v_mfma_f32_32x32x16_bf16 v[82:97], v[138:141], v[218:221], 0
	ds_read_b128 v[138:141], v212 offset:17440
	v_mfma_f32_32x32x16_bf16 v[82:97], v[170:173], v[222:225], v[82:97]
	ds_read_b128 v[170:173], v212 offset:17472
	v_mfma_f32_32x32x16_bf16 v[82:97], v[142:145], v[226:229], v[82:97]
	v_lshlrev_b32_e32 v114, 16, v114
	s_waitcnt lgkmcnt(14)
	v_lshlrev_b32_e32 v115, 16, v115
	s_waitcnt lgkmcnt(13)
	v_lshlrev_b32_e32 v116, 16, v116
	s_waitcnt lgkmcnt(12)
	v_lshlrev_b32_e32 v117, 16, v117
	s_waitcnt lgkmcnt(10)
	v_fma_f32 v114, -v66, v122, v114
	v_fma_f32 v115, -v67, v123, v115
	v_fma_f32 v116, -v68, v124, v116
	v_fma_f32 v117, -v69, v125, v117
	v_mul_f32_e32 v66, v118, v114
	v_mul_f32_e32 v67, v119, v115
	v_mul_f32_e32 v68, v120, v116
	v_mul_f32_e32 v69, v121, v117
	ds_read_u16 v114, v213 offset:38912
	ds_read_u16 v115, v213 offset:39168
	ds_read_u16 v116, v213 offset:39424
	ds_read_u16 v117, v213 offset:39680
	ds_read_b128 v[118:121], v214 offset:64
	ds_read_b128 v[122:125], v214 offset:576
	ds_read_b128 v[142:145], v212 offset:17504
	v_mfma_f32_32x32x16_bf16 v[82:97], v[146:149], v[230:233], v[82:97]
	v_lshlrev_b32_e32 v126, 16, v126
	v_lshlrev_b32_e32 v127, 16, v127
	s_waitcnt lgkmcnt(14)
	v_lshlrev_b32_e32 v128, 16, v128
	s_waitcnt lgkmcnt(13)
	v_lshlrev_b32_e32 v129, 16, v129
	s_waitcnt lgkmcnt(11)
	v_fma_f32 v126, -v70, v134, v126
	v_fma_f32 v127, -v71, v135, v127
	v_fma_f32 v128, -v72, v136, v128
	v_fma_f32 v129, -v73, v137, v129
	v_mul_f32_e32 v70, v130, v126
	v_mul_f32_e32 v71, v131, v127
	v_mul_f32_e32 v72, v132, v128
	v_mul_f32_e32 v73, v133, v129
	ds_read_u16 v126, v213 offset:40960
	ds_read_u16 v127, v213 offset:41216
	ds_read_u16 v128, v213 offset:41472
	ds_read_u16 v129, v213 offset:41728
	ds_read_b128 v[130:133], v214 offset:96
	ds_read_b128 v[134:137], v214 offset:608
	ds_read_b128 v[146:149], v212 offset:17536
	v_mfma_f32_32x32x16_bf16 v[82:97], v[150:153], v[234:237], v[82:97]
	v_cvt_pk_bf16_f32 v150, v66, v67
	v_cvt_pk_bf16_f32 v152, v70, v71
	v_cvt_pk_bf16_f32 v151, v68, v69
	v_cvt_pk_bf16_f32 v153, v72, v73
	v_permlane32_swap_b32_e32 v150, v152
	s_nop 0
	v_permlane32_swap_b32_e32 v151, v153
	s_waitcnt lgkmcnt(13)
	v_lshlrev_b32_e32 v114, 16, v114
	s_waitcnt lgkmcnt(12)
	v_lshlrev_b32_e32 v115, 16, v115
	s_waitcnt lgkmcnt(11)
	v_lshlrev_b32_e32 v116, 16, v116
	s_waitcnt lgkmcnt(10)
	v_lshlrev_b32_e32 v117, 16, v117
	s_waitcnt lgkmcnt(8)
	v_fma_f32 v114, -v74, v122, v114
	v_fma_f32 v115, -v75, v123, v115
	v_fma_f32 v116, -v76, v124, v116
	v_fma_f32 v117, -v77, v125, v117
	v_mul_f32_e32 v74, v118, v114
	v_mul_f32_e32 v75, v119, v115
	v_mul_f32_e32 v76, v120, v116
	v_mul_f32_e32 v77, v121, v117
	v_mfma_f32_32x32x16_bf16 v[82:97], v[154:157], v[238:241], v[82:97]
	s_waitcnt lgkmcnt(6)
	v_lshlrev_b32_e32 v126, 16, v126
	s_waitcnt lgkmcnt(5)
	v_lshlrev_b32_e32 v127, 16, v127
	s_waitcnt lgkmcnt(4)
	v_lshlrev_b32_e32 v128, 16, v128
	s_waitcnt lgkmcnt(3)
	v_lshlrev_b32_e32 v129, 16, v129
	s_waitcnt lgkmcnt(1)
; #define LAS __attribute__((address_space(3)))
; #define MFMA32(a, b, c) __builtin_amdgcn_mfma_f32_32x32x16_bf16((a), (b), (c), 0, 0, 0)
; template <int VAR> __device__ __forceinline__ void dn_scan3(LAS unsigned char* lds, const bf16_t* P, const float* AB, const bf16_t* TP, bf16_t* OB) {
;     ...
;                 for (int ks = 0; ks < 8; ++ks) {
;                     const bf16x8 sp = pack_step(S[ks >> 1], ks & 1);
; #pragma unroll
;                     for (int mt = 0; mt < 2; ++mt) { KS[mt] = MFMA32(frag_perm(Kb, 136, 32 * mt + r, ks, h), sp, KS[mt]); QS[mt] = MFMA32(frag_perm(Qb, 136, 32 * mt + r, ks, h), sp, QS[mt]); }
;                 }
;                 __builtin_amdgcn_iglp_opt(0);
; #pragma unroll
;                 for (int mt = 0; mt < 2; ++mt)
; #pragma unroll
;                     for (int g4 = 0; g4 < 4; ++g4) { const int i0 = 32 * mt + 8 * g4 + 4 * h;
;                         const f32x4 bv = *(const LAS f32x4*)(sc_beta + i0), ev = *(const LAS f32x4*)(sc_eg + i0);
; #pragma unroll
;                         for (int e = 0; e < 4; ++e) { const int x = 4 * g4 + e; KS[mt][x] = bv[e] * (bf2f(Vb[(i0 + e) * 128 + 32 * w + r]) - ev[e] * KS[mt][x]); } }
;                 bf16x8 Xp[4];
; #pragma unroll
;                 for (int ks = 0; ks < 4; ++ks) Xp[ks] = pack_step(KS[ks >> 1], ks & 1);
;     ...
;                 const float dl = sc_dl[0];
; #pragma unroll
;                 for (int kt = 0; kt < 4; ++kt)
; #pragma unroll
;                     for (int x = 0; x < 16; ++x) S[kt][x] *= dl;
	v_fma_f32 v126, -v78, v134, v126
	v_fma_f32 v127, -v79, v135, v127
	v_fma_f32 v128, -v80, v136, v128
	v_fma_f32 v129, -v81, v137, v129
	v_mul_f32_e32 v78, v130, v126
	v_mul_f32_e32 v79, v131, v127
	v_mul_f32_e32 v80, v132, v128
	v_mul_f32_e32 v81, v133, v129
	ds_read_u16 v114, v213 offset:43008
	ds_read_u16 v115, v213 offset:43264
	ds_read_u16 v116, v213 offset:43520
	ds_read_u16 v117, v213 offset:43776
	ds_read_b128 v[118:121], v214 offset:128
	ds_read_b128 v[122:125], v214 offset:640
	ds_read_b128 v[154:157], v212 offset:17568
	v_mfma_f32_32x32x16_bf16 v[82:97], v[158:161], v[242:245], v[82:97]
	v_cvt_pk_bf16_f32 v158, v74, v75
	v_cvt_pk_bf16_f32 v160, v78, v79
	v_cvt_pk_bf16_f32 v159, v76, v77
	v_cvt_pk_bf16_f32 v161, v80, v81
	v_permlane32_swap_b32_e32 v158, v160
	s_nop 0
	v_permlane32_swap_b32_e32 v159, v161
	ds_read_u16 v126, v213 offset:45056
	ds_read_u16 v127, v213 offset:45312
	ds_read_u16 v128, v213 offset:45568
	ds_read_u16 v129, v213 offset:45824
	ds_read_b128 v[130:133], v214 offset:160
	ds_read_b128 v[134:137], v214 offset:672
	v_mfma_f32_32x32x16_bf16 v[82:97], v[162:165], v[246:249], v[82:97]
	ds_read_b128 v[162:165], v212 offset:17600
	v_mfma_f32_32x32x16_bf16 v[98:113], v[166:169], v[218:221], 0
	ds_read_b128 v[166:169], v212 offset:17632
	v_mfma_f32_32x32x16_bf16 v[98:113], v[138:141], v[222:225], v[98:113]
	ds_read_b128 v[138:141], v212 offset:26112
	v_mfma_f32_32x32x16_bf16 v[98:113], v[170:173], v[226:229], v[98:113]
	v_lshlrev_b32_e32 v114, 16, v114
	s_waitcnt lgkmcnt(14)
	v_lshlrev_b32_e32 v115, 16, v115
	s_waitcnt lgkmcnt(13)
	v_lshlrev_b32_e32 v116, 16, v116
	s_waitcnt lgkmcnt(12)
	v_lshlrev_b32_e32 v117, 16, v117
	s_waitcnt lgkmcnt(10)
	v_fma_f32 v114, -v82, v122, v114
	v_fma_f32 v115, -v83, v123, v115
	v_fma_f32 v116, -v84, v124, v116
	v_fma_f32 v117, -v85, v125, v117
	v_mul_f32_e32 v82, v118, v114
	v_mul_f32_e32 v83, v119, v115
	v_mul_f32_e32 v84, v120, v116
	v_mul_f32_e32 v85, v121, v117
	ds_read_u16 v114, v213 offset:47104
	ds_read_u16 v115, v213 offset:47360
	ds_read_u16 v116, v213 offset:47616
	ds_read_u16 v117, v213 offset:47872
	ds_read_b128 v[118:121], v214 offset:192
	ds_read_b128 v[122:125], v214 offset:704
	ds_read_b128 v[170:173], v212 offset:26144
	v_mfma_f32_32x32x16_bf16 v[98:113], v[142:145], v[230:233], v[98:113]
	v_lshlrev_b32_e32 v126, 16, v126
	s_waitcnt lgkmcnt(14)
	v_lshlrev_b32_e32 v127, 16, v127
	s_waitcnt lgkmcnt(13)
	v_lshlrev_b32_e32 v128, 16, v128
	s_waitcnt lgkmcnt(12)
	v_lshlrev_b32_e32 v129, 16, v129
	s_waitcnt lgkmcnt(10)
	v_fma_f32 v126, -v86, v134, v126
	v_fma_f32 v127, -v87, v135, v127
	v_fma_f32 v128, -v88, v136, v128
	v_fma_f32 v129, -v89, v137, v129
	v_mul_f32_e32 v86, v130, v126
	v_mul_f32_e32 v87, v131, v127
	v_mul_f32_e32 v88, v132, v128
	v_mul_f32_e32 v89, v133, v129
	ds_read_u16 v126, v213 offset:49152
	ds_read_u16 v127, v213 offset:49408
	ds_read_u16 v128, v213 offset:49664
	ds_read_u16 v129, v213 offset:49920
	ds_read_b128 v[130:133], v214 offset:224
	ds_read_b128 v[134:137], v214 offset:736
	ds_read_b128 v[142:145], v212 offset:26176
	v_mfma_f32_32x32x16_bf16 v[98:113], v[146:149], v[234:237], v[98:113]
	v_cvt_pk_bf16_f32 v146, v82, v83
	v_cvt_pk_bf16_f32 v148, v86, v87
	v_cvt_pk_bf16_f32 v147, v84, v85
	v_cvt_pk_bf16_f32 v149, v88, v89
	v_permlane32_swap_b32_e32 v146, v148
	s_nop 0
	v_permlane32_swap_b32_e32 v147, v149
	s_waitcnt lgkmcnt(13)
	v_lshlrev_b32_e32 v114, 16, v114
	s_waitcnt lgkmcnt(12)
	v_lshlrev_b32_e32 v115, 16, v115
	s_waitcnt lgkmcnt(11)
	v_lshlrev_b32_e32 v116, 16, v116
	s_waitcnt lgkmcnt(10)
	v_lshlrev_b32_e32 v117, 16, v117
	s_waitcnt lgkmcnt(8)
	v_fma_f32 v114, -v90, v122, v114
	v_fma_f32 v115, -v91, v123, v115
	v_fma_f32 v116, -v92, v124, v116
	v_fma_f32 v117, -v93, v125, v117
	v_mul_f32_e32 v90, v118, v114
	v_mul_f32_e32 v91, v119, v115
	v_mul_f32_e32 v92, v120, v116
	v_mul_f32_e32 v93, v121, v117
	v_mfma_f32_32x32x16_bf16 v[98:113], v[154:157], v[238:241], v[98:113]
	s_waitcnt lgkmcnt(6)
	v_lshlrev_b32_e32 v126, 16, v126
	s_waitcnt lgkmcnt(5)
	v_lshlrev_b32_e32 v127, 16, v127
	s_waitcnt lgkmcnt(4)
	v_lshlrev_b32_e32 v128, 16, v128
	s_waitcnt lgkmcnt(3)
	v_lshlrev_b32_e32 v129, 16, v129
	s_waitcnt lgkmcnt(1)
	v_fma_f32 v126, -v94, v134, v126
	v_fma_f32 v127, -v95, v135, v127
	v_fma_f32 v128, -v96, v136, v128
	v_fma_f32 v129, -v97, v137, v129
	v_mul_f32_e32 v94, v130, v126
	v_mul_f32_e32 v95, v131, v127
	v_mul_f32_e32 v96, v132, v128
	v_mul_f32_e32 v97, v133, v129
	ds_read_b128 v[154:157], v212 offset:26208
	v_mfma_f32_32x32x16_bf16 v[98:113], v[162:165], v[242:245], v[98:113]
	v_cvt_pk_bf16_f32 v162, v90, v91
	v_cvt_pk_bf16_f32 v164, v94, v95
	v_cvt_pk_bf16_f32 v163, v92, v93
	v_cvt_pk_bf16_f32 v165, v96, v97
	v_permlane32_swap_b32_e32 v162, v164
	s_nop 0
	v_permlane32_swap_b32_e32 v163, v165
	v_mfma_f32_32x32x16_bf16 v[98:113], v[166:169], v[246:249], v[98:113]
	ds_read_b32 v130, v217
	ds_read_b128 v[134:137], v214 offset:512
	ds_read_b128 v[166:169], v212 offset:26240
	v_mfma_f32_32x32x16_bf16 v[114:129], v[138:141], v[218:221], 0
	s_waitcnt lgkmcnt(2)
	v_mul_f32_e32 v50, v50, v130
	v_mul_f32_e32 v51, v51, v130
	v_mul_f32_e32 v52, v52, v130
	v_mul_f32_e32 v53, v53, v130
	v_mul_f32_e32 v54, v54, v130
	v_mul_f32_e32 v55, v55, v130
	v_mul_f32_e32 v56, v56, v130
	v_mul_f32_e32 v57, v57, v130
	ds_read_b128 v[138:141], v214 offset:544
	v_mfma_f32_32x32x16_bf16 v[114:129], v[170:173], v[222:225], v[114:129]
	v_mul_f32_e32 v58, v58, v130
	v_mul_f32_e32 v59, v59, v130
	v_mul_f32_e32 v60, v60, v130
	v_mul_f32_e32 v61, v61, v130
	v_mul_f32_e32 v62, v62, v130
	v_mul_f32_e32 v63, v63, v130
	v_mul_f32_e32 v64, v64, v130
	v_mul_f32_e32 v65, v65, v130
	v_mul_f32_e32 v34, v34, v130
	v_mul_f32_e32 v35, v35, v130
	s_waitcnt lgkmcnt(2)
; __device__ __forceinline__ int crow(int r, int hi) { return (r & 3) + 8 * (r >> 2) + 4 * hi; }
; #define LAS __attribute__((address_space(3)))
; template <int VAR> __device__ __forceinline__ void dn_scan3(LAS unsigned char* lds, const bf16_t* P, const float* AB, const bf16_t* TP, bf16_t* OB) {
;     ...
;                 f32x16 VN[2];
; #pragma unroll
;                 for (int mt = 0; mt < 2; ++mt) {
; #pragma unroll
;                     for (int x = 0; x < 16; ++x) VN[mt][x] = 0.f;
; #pragma unroll
;                     for (int ks = 0; ks < 4; ++ks) if (ks < 2 * mt + 2) VN[mt] = MFMA32(frag_perm(Tb, 72, 32 * mt + r, ks, h), Xp[ks], VN[mt]);
;                 }
;                 bf16x8 VNp[4];
; #pragma unroll
;                 for (int ks = 0; ks < 4; ++ks) VNp[ks] = pack_step(VN[ks >> 1], ks & 1);
; #pragma unroll
;                 for (int mt = 0; mt < 2; ++mt) {
; #pragma unroll
;                     for (int g4 = 0; g4 < 4; ++g4) { const f32x4 ev = *(const LAS f32x4*)(sc_eg + 32 * mt + 8 * g4 + 4 * h);
; #pragma unroll
;                         for (int e = 0; e < 4; ++e) QS[mt][4 * g4 + e] *= ev[e]; }
; #pragma unroll
;                     for (int ks = 0; ks < 4; ++ks) if (ks < 2 * mt + 2) QS[mt] = MFMA32(frag_perm(Ab, 72, 32 * mt + r, ks, h), VNp[ks], QS[mt]);
;                 }
; #pragma unroll
;                 for (int mt = 0; mt < 2; ++mt)
; #pragma unroll
;                     for (int x = 0; x < 16; ++x) Vb[(32 * mt + crow(x, h)) * 128 + 32 * w + r] = f2bf(QS[mt][x]);
; #pragma unroll
;                 for (int mt = 0; mt < 2; ++mt)
; #pragma unroll
;                     for (int g4 = 0; g4 < 4; ++g4) { const f32x4 tv = *(const LAS f32x4*)(sc_tail + 32 * mt + 8 * g4 + 4 * h);
; #pragma unroll
;                         for (int e = 0; e < 4; ++e) VN[mt][4 * g4 + e] *= tv[e]; }
; #pragma unroll
;                 for (int ks = 0; ks < 4; ++ks) VNp[ks] = pack_step(VN[ks >> 1], ks & 1);
;                 const float dl = sc_dl[0];
; #pragma unroll
;                 for (int kt = 0; kt < 4; ++kt)
; #pragma unroll
;                     for (int x = 0; x < 16; ++x) S[kt][x] *= dl;
; #pragma unroll
;                 for (int ks = 0; ks < 4; ++ks) {
; #pragma unroll
;                     for (int kt = 0; kt < 4; ++kt) S[kt] = MFMA32(frag_tr(Kb, 136, 32 * kt, ks, lane), VNp[ks], S[kt]);
	v_mul_f32_e32 v98, v98, v134
	v_mul_f32_e32 v99, v99, v135
	v_mul_f32_e32 v100, v100, v136
	v_mul_f32_e32 v101, v101, v137
	ds_read_b128 v[134:137], v214 offset:576
	ds_read_b128 v[170:173], v212 offset:26272
	v_mfma_f32_32x32x16_bf16 v[114:129], v[142:145], v[226:229], v[114:129]
	v_mul_f32_e32 v36, v36, v130
	v_mul_f32_e32 v37, v37, v130
	v_mul_f32_e32 v38, v38, v130
	v_mul_f32_e32 v39, v39, v130
	v_mul_f32_e32 v40, v40, v130
	v_mul_f32_e32 v41, v41, v130
	v_mul_f32_e32 v42, v42, v130
	v_mul_f32_e32 v43, v43, v130
	v_mul_f32_e32 v44, v44, v130
	v_mul_f32_e32 v45, v45, v130
	s_waitcnt lgkmcnt(2)
	v_mul_f32_e32 v102, v102, v138
	v_mul_f32_e32 v103, v103, v139
	v_mul_f32_e32 v104, v104, v140
	v_mul_f32_e32 v105, v105, v141
	ds_read_b128 v[138:141], v214 offset:608
	ds_read_b128 v[142:145], v212 offset:26304
	v_mfma_f32_32x32x16_bf16 v[114:129], v[154:157], v[230:233], v[114:129]
	v_mul_f32_e32 v46, v46, v130
	v_mul_f32_e32 v47, v47, v130
	v_mul_f32_e32 v48, v48, v130
	v_mul_f32_e32 v49, v49, v130
	v_mul_f32_e32 v18, v18, v130
	v_mul_f32_e32 v19, v19, v130
	v_mul_f32_e32 v20, v20, v130
	v_mul_f32_e32 v21, v21, v130
	v_mul_f32_e32 v22, v22, v130
	v_mul_f32_e32 v23, v23, v130
	s_waitcnt lgkmcnt(3)
	v_mul_f32_e32 v106, v106, v134
	v_mul_f32_e32 v107, v107, v135
	v_mul_f32_e32 v108, v108, v136
	v_mul_f32_e32 v109, v109, v137
	ds_read_b128 v[154:157], v212 offset:26336
	v_mfma_f32_32x32x16_bf16 v[114:129], v[166:169], v[234:237], v[114:129]
	v_mul_f32_e32 v24, v24, v130
	v_mul_f32_e32 v25, v25, v130
	v_mul_f32_e32 v26, v26, v130
	v_mul_f32_e32 v27, v27, v130
	v_mul_f32_e32 v28, v28, v130
	v_mul_f32_e32 v29, v29, v130
	v_mul_f32_e32 v30, v30, v130
	v_mul_f32_e32 v31, v31, v130
	v_mul_f32_e32 v32, v32, v130
	v_mul_f32_e32 v33, v33, v130
	s_waitcnt lgkmcnt(2)
	v_mul_f32_e32 v110, v110, v138
	v_mul_f32_e32 v111, v111, v139
	v_mul_f32_e32 v112, v112, v140
	v_mul_f32_e32 v113, v113, v141
	ds_read_b128 v[134:137], v215 offset:51200
	ds_read_b128 v[138:141], v215 offset:51232
	v_mfma_f32_32x32x16_bf16 v[114:129], v[170:173], v[238:241], v[114:129]
	v_mul_f32_e32 v2, v2, v130
	v_mul_f32_e32 v3, v3, v130
	v_mul_f32_e32 v4, v4, v130
	v_mul_f32_e32 v5, v5, v130
	v_mul_f32_e32 v6, v6, v130
	v_mul_f32_e32 v7, v7, v130
	v_mul_f32_e32 v8, v8, v130
	v_mul_f32_e32 v9, v9, v130
	ds_read_b128 v[166:169], v215 offset:55808
	ds_read_b128 v[170:173], v215 offset:55840
	s_waitcnt lgkmcnt(5)
	v_mfma_f32_32x32x16_bf16 v[114:129], v[142:145], v[242:245], v[114:129]
	v_mul_f32_e32 v10, v10, v130
	v_mul_f32_e32 v11, v11, v130
	v_mul_f32_e32 v12, v12, v130
	v_mul_f32_e32 v13, v13, v130
	v_mul_f32_e32 v14, v14, v130
	v_mul_f32_e32 v15, v15, v130
	v_mul_f32_e32 v16, v16, v130
	v_mul_f32_e32 v17, v17, v130
	ds_read_b128 v[142:145], v215 offset:55872
	ds_read_b128 v[174:177], v215 offset:55904
	s_waitcnt lgkmcnt(6)
	v_mfma_f32_32x32x16_bf16 v[114:129], v[154:157], v[246:249], v[114:129]
	ds_read_b128 v[130:133], v214 offset:640
	ds_read_b128 v[154:157], v214 offset:672
	s_waitcnt lgkmcnt(7)
	v_mfma_f32_32x32x16_bf16 v[66:81], v[134:137], v[150:153], 0
	ds_read_b128 v[134:137], v214 offset:704
	ds_read_b128 v[218:221], v214 offset:736
	s_waitcnt lgkmcnt(8)
	v_mfma_f32_32x32x16_bf16 v[66:81], v[138:141], v[158:161], v[66:81]
	ds_read_b128 v[138:141], v214 offset:768
	ds_read_b128 v[222:225], v214 offset:800
	s_waitcnt lgkmcnt(9)
	v_mfma_f32_32x32x16_bf16 v[82:97], v[166:169], v[150:153], 0
	ds_read_b128 v[150:153], v214 offset:832
	ds_read_b128 v[166:169], v214 offset:864
	s_waitcnt lgkmcnt(10)
	v_mfma_f32_32x32x16_bf16 v[82:97], v[170:173], v[158:161], v[82:97]
	s_waitcnt lgkmcnt(7)
	v_mul_f32_e32 v114, v114, v130
	v_mul_f32_e32 v115, v115, v131
	v_mul_f32_e32 v116, v116, v132
	v_mul_f32_e32 v117, v117, v133
	s_waitcnt lgkmcnt(6)
	v_mul_f32_e32 v118, v118, v154
	v_mul_f32_e32 v119, v119, v155
	v_mul_f32_e32 v120, v120, v156
	v_mul_f32_e32 v121, v121, v157
	ds_read_b128 v[130:133], v215 offset:60416
	ds_read_b128 v[154:157], v215 offset:60448
	v_mfma_f32_32x32x16_bf16 v[82:97], v[142:145], v[146:149], v[82:97]
	s_waitcnt lgkmcnt(7)
	v_mul_f32_e32 v122, v122, v134
	v_mul_f32_e32 v123, v123, v135
	v_mul_f32_e32 v124, v124, v136
	v_mul_f32_e32 v125, v125, v137
	s_waitcnt lgkmcnt(6)
	v_mul_f32_e32 v126, v126, v218
	v_mul_f32_e32 v127, v127, v219
	v_mul_f32_e32 v128, v128, v220
	v_mul_f32_e32 v129, v129, v221
	v_mfma_f32_32x32x16_bf16 v[82:97], v[174:177], v[162:165], v[82:97]
	v_add_u32_e32 v134, s41, v211
	v_add_u32_e32 v135, s41, v201
	v_and_b32_e32 v136, 0xffff, v180
	v_lshrrev_b32_e32 v137, 16, v180
	v_add_u32_e32 v136, s41, v136
	v_add_u32_e32 v137, s41, v137
	ds_read_b64_tr_b16 v[158:159], v134 offset:0
	ds_read_b64_tr_b16 v[160:161], v135 offset:0
	ds_read_b64_tr_b16 v[162:163], v134 offset:64
	ds_read_b64_tr_b16 v[164:165], v135 offset:64
	v_cvt_pk_bf16_f32 v142, v66, v67
	v_cvt_pk_bf16_f32 v144, v70, v71
	v_cvt_pk_bf16_f32 v143, v68, v69
	v_cvt_pk_bf16_f32 v145, v72, v73
	v_cvt_pk_bf16_f32 v146, v74, v75
	v_cvt_pk_bf16_f32 v148, v78, v79
	v_cvt_pk_bf16_f32 v147, v76, v77
	v_cvt_pk_bf16_f32 v149, v80, v81
	v_permlane32_swap_b32_e32 v142, v144
	v_permlane32_swap_b32_e32 v143, v145
	v_permlane32_swap_b32_e32 v146, v148
	v_permlane32_swap_b32_e32 v147, v149
	s_waitcnt lgkmcnt(9)
	v_mul_f32_e32 v66, v66, v138
	v_mul_f32_e32 v67, v67, v139
	v_mul_f32_e32 v68, v68, v140
	v_mul_f32_e32 v69, v69, v141
	s_waitcnt lgkmcnt(8)
	v_mul_f32_e32 v70, v70, v222
	v_mul_f32_e32 v71, v71, v223
	v_mul_f32_e32 v72, v72, v224
	v_mul_f32_e32 v73, v73, v225
	s_waitcnt lgkmcnt(7)
	v_mul_f32_e32 v74, v74, v150
	v_mul_f32_e32 v75, v75, v151
	v_mul_f32_e32 v76, v76, v152
	v_mul_f32_e32 v77, v77, v153
	s_waitcnt lgkmcnt(6)
; __device__ __forceinline__ int crow(int r, int hi) { return (r & 3) + 8 * (r >> 2) + 4 * hi; }
; #define LAS __attribute__((address_space(3)))
; __device__ __forceinline__ bf16_t f2bf(float f) { return (bf16_t)(cvtpk_s(f, 0.f) & 0xffffu); }
; __device__ __forceinline__ int crow(int x, int h) { return (x & 3) + 8 * (x >> 2) + 4 * h; }
; #define MFMA32(a, b, c) __builtin_amdgcn_mfma_f32_32x32x16_bf16((a), (b), (c), 0, 0, 0)
; template <int VAR> __device__ __forceinline__ void dn_scan3(LAS unsigned char* lds, const bf16_t* P, const float* AB, const bf16_t* TP, bf16_t* OB) {
;     ...
; #pragma unroll
;                 for (int mt = 0; mt < 2; ++mt)
; #pragma unroll
;                     for (int x = 0; x < 16; ++x) Vb[(32 * mt + crow(x, h)) * 128 + 32 * w + r] = f2bf(QS[mt][x]);
; #pragma unroll
;                 for (int mt = 0; mt < 2; ++mt)
; #pragma unroll
;                     for (int g4 = 0; g4 < 4; ++g4) { const f32x4 tv = *(const LAS f32x4*)(sc_tail + 32 * mt + 8 * g4 + 4 * h);
; #pragma unroll
;                         for (int e = 0; e < 4; ++e) VN[mt][4 * g4 + e] *= tv[e]; }
; #pragma unroll
;                 for (int ks = 0; ks < 4; ++ks) VNp[ks] = pack_step(VN[ks >> 1], ks & 1);
;                 const float dl = sc_dl[0];
; #pragma unroll
;                 for (int kt = 0; kt < 4; ++kt)
; #pragma unroll
;                     for (int x = 0; x < 16; ++x) S[kt][x] *= dl;
; #pragma unroll
;                 for (int ks = 0; ks < 4; ++ks) {
; #pragma unroll
;                     for (int kt = 0; kt < 4; ++kt) S[kt] = MFMA32(frag_tr(Kb, 136, 32 * kt, ks, lane), VNp[ks], S[kt]);
	v_mul_f32_e32 v78, v78, v166
	v_mul_f32_e32 v79, v79, v167
	v_mul_f32_e32 v80, v80, v168
	v_mul_f32_e32 v81, v81, v169
	v_cvt_pk_bf16_f32 v138, v66, v71
	v_cvt_pk_bf16_f32 v139, v76, v81
	v_cvt_pk_bf16_f32 v140, v67, v72
	v_cvt_pk_bf16_f32 v141, v77, v78
	v_cvt_pk_bf16_f32 v150, v68, v73
	v_cvt_pk_bf16_f32 v151, v74, v79
	v_cvt_pk_bf16_f32 v152, v69, v70
	v_cvt_pk_bf16_f32 v153, v75, v80
	ds_read_b64_tr_b16 v[166:167], v134 offset:128
	ds_read_b64_tr_b16 v[168:169], v135 offset:128
	ds_read_b64_tr_b16 v[170:171], v134 offset:192
	ds_read_b64_tr_b16 v[172:173], v135 offset:192
	ds_read_b64_tr_b16 v[174:175], v136 offset:0
	ds_read_b64_tr_b16 v[176:177], v137 offset:0
	ds_read_b64_tr_b16 v[218:219], v136 offset:64
	ds_read_b64_tr_b16 v[220:221], v137 offset:64
	s_waitcnt lgkmcnt(13)
	v_mfma_f32_32x32x16_bf16 v[98:113], v[130:133], v[142:145], v[98:113]
	ds_read_b128 v[130:133], v215 offset:65024
	ds_read_b128 v[222:225], v215 offset:65056
	s_waitcnt lgkmcnt(14)
	v_mfma_f32_32x32x16_bf16 v[98:113], v[154:157], v[146:149], v[98:113]
	ds_read_b128 v[154:157], v214 offset:896
	ds_read_b128 v[226:229], v214 offset:928
	ds_read_b64_tr_b16 v[230:231], v136 offset:128
	ds_read_b64_tr_b16 v[232:233], v137 offset:128
	ds_read_b64_tr_b16 v[234:235], v136 offset:192
	ds_read_b64_tr_b16 v[236:237], v137 offset:192
	ds_read_b64_tr_b16 v[238:239], v134 offset:8704
	ds_read_b64_tr_b16 v[240:241], v135 offset:8704
	v_mfma_f32_32x32x16_bf16 v[50:65], v[158:161], v[138:141], v[50:65]
	ds_read_b128 v[158:161], v214 offset:960
	ds_read_b128 v[242:245], v214 offset:992
	v_mfma_f32_32x32x16_bf16 v[34:49], v[162:165], v[138:141], v[34:49]
	v_cvt_pk_bf16_f32 v162, v82, v83
	v_cvt_pk_bf16_f32 v164, v86, v87
	v_cvt_pk_bf16_f32 v163, v84, v85
	v_cvt_pk_bf16_f32 v165, v88, v89
	v_permlane32_swap_b32_e32 v162, v164
	s_nop 0
	v_permlane32_swap_b32_e32 v163, v165
	v_mfma_f32_32x32x16_bf16 v[18:33], v[166:169], v[138:141], v[18:33]
	v_cvt_pk_bf16_f32 v166, v90, v91
	v_cvt_pk_bf16_f32 v168, v94, v95
	v_cvt_pk_bf16_f32 v167, v92, v93
	v_cvt_pk_bf16_f32 v169, v96, v97
	v_permlane32_swap_b32_e32 v166, v168
	s_nop 0
	v_permlane32_swap_b32_e32 v167, v169
	v_mfma_f32_32x32x16_bf16 v[2:17], v[170:173], v[138:141], v[2:17]
	s_waitcnt lgkmcnt(9)
	v_mul_f32_e32 v82, v82, v154
	v_mul_f32_e32 v83, v83, v155
	v_mul_f32_e32 v84, v84, v156
	v_mul_f32_e32 v85, v85, v157
	s_waitcnt lgkmcnt(8)
	v_mul_f32_e32 v86, v86, v226
	v_mul_f32_e32 v87, v87, v227
	v_mul_f32_e32 v88, v88, v228
	v_mul_f32_e32 v89, v89, v229
	ds_read_b128 v[154:157], v215 offset:65088
	ds_read_b128 v[170:173], v215 offset:65120
	v_mfma_f32_32x32x16_bf16 v[50:65], v[174:177], v[150:153], v[50:65]
	v_cvt_pk_bf16_f32 v174, v98, s0
	ds_write_b16 v213, v174 offset:34816
	v_cvt_pk_bf16_f32 v175, v99, s0
	ds_write_b16 v213, v175 offset:35072
	s_waitcnt lgkmcnt(5)
	v_mul_f32_e32 v90, v90, v158
	v_mul_f32_e32 v91, v91, v159
	v_mul_f32_e32 v92, v92, v160
	v_mul_f32_e32 v93, v93, v161
	s_waitcnt lgkmcnt(4)
	v_mul_f32_e32 v94, v94, v242
	v_mul_f32_e32 v95, v95, v243
	v_mul_f32_e32 v96, v96, v244
	v_mul_f32_e32 v97, v97, v245
	ds_read_b64_tr_b16 v[158:159], v134 offset:8768
	ds_read_b64_tr_b16 v[160:161], v135 offset:8768
	v_mfma_f32_32x32x16_bf16 v[34:49], v[218:221], v[150:153], v[34:49]
	v_cvt_pk_bf16_f32 v176, v100, s0
	ds_write_b16 v213, v176 offset:35328
	v_cvt_pk_bf16_f32 v177, v101, s0
	ds_write_b16 v213, v177 offset:35584
	v_cvt_pk_bf16_f32 v218, v82, v87
	v_cvt_pk_bf16_f32 v219, v92, v97
	v_cvt_pk_bf16_f32 v220, v83, v88
	v_cvt_pk_bf16_f32 v221, v93, v94
	ds_read_b64_tr_b16 v[226:227], v134 offset:8832
	ds_read_b64_tr_b16 v[228:229], v135 offset:8832
	v_mfma_f32_32x32x16_bf16 v[18:33], v[230:233], v[150:153], v[18:33]
	v_cvt_pk_bf16_f32 v174, v102, s0
	ds_write_b16 v213, v174 offset:36864
	v_cvt_pk_bf16_f32 v175, v103, s0
	ds_write_b16 v213, v175 offset:37120
	v_cvt_pk_bf16_f32 v230, v84, v89
	v_cvt_pk_bf16_f32 v231, v90, v95
	v_cvt_pk_bf16_f32 v232, v85, v86
	v_cvt_pk_bf16_f32 v233, v91, v96
	v_mfma_f32_32x32x16_bf16 v[2:17], v[234:237], v[150:153], v[2:17]
	v_cvt_pk_bf16_f32 v176, v104, s0
	ds_write_b16 v213, v176 offset:37376
	v_cvt_pk_bf16_f32 v177, v105, s0
	ds_write_b16 v213, v177 offset:37632
	v_mfma_f32_32x32x16_bf16 v[114:129], v[130:133], v[142:145], v[114:129]
	v_cvt_pk_bf16_f32 v174, v106, s0
	ds_write_b16 v213, v174 offset:38912
	v_cvt_pk_bf16_f32 v175, v107, s0
	ds_write_b16 v213, v175 offset:39168
	ds_read_b64_tr_b16 v[130:131], v134 offset:8896
	ds_read_b64_tr_b16 v[132:133], v135 offset:8896
	ds_read_b64_tr_b16 v[138:139], v136 offset:8704
	ds_read_b64_tr_b16 v[140:141], v137 offset:8704
	v_mfma_f32_32x32x16_bf16 v[114:129], v[222:225], v[146:149], v[114:129]
	v_cvt_pk_bf16_f32 v176, v108, s0
	ds_write_b16 v213, v176 offset:39424
	v_cvt_pk_bf16_f32 v177, v109, s0
	ds_write_b16 v213, v177 offset:39680
	ds_read_b64_tr_b16 v[142:143], v136 offset:8768
	ds_read_b64_tr_b16 v[144:145], v137 offset:8768
	ds_read_b64_tr_b16 v[146:147], v136 offset:8832
	ds_read_b64_tr_b16 v[148:149], v137 offset:8832
	v_mfma_f32_32x32x16_bf16 v[114:129], v[154:157], v[162:165], v[114:129]
	v_cvt_pk_bf16_f32 v174, v110, s0
	ds_write_b16 v213, v174 offset:40960
	v_cvt_pk_bf16_f32 v175, v111, s0
	ds_write_b16 v213, v175 offset:41216
	ds_read_b64_tr_b16 v[150:151], v136 offset:8896
	ds_read_b64_tr_b16 v[152:153], v137 offset:8896
	v_mfma_f32_32x32x16_bf16 v[114:129], v[170:173], v[166:169], v[114:129]
	v_cvt_pk_bf16_f32 v176, v112, s0
	ds_write_b16 v213, v176 offset:41472
	v_cvt_pk_bf16_f32 v177, v113, s0
	ds_write_b16 v213, v177 offset:41728
	ds_read_b32 v154, v179 offset:34816
	ds_read_b32 v155, v179 offset:35840
	ds_read_b32 v156, v179 offset:36864
	ds_read_b32 v157, v179 offset:37888
	ds_read_b32 v162, v179 offset:38912
	ds_read_b32 v163, v179 offset:39936
	ds_read_b32 v164, v179 offset:40960
	ds_read_b32 v165, v179 offset:41984
	v_mfma_f32_32x32x16_bf16 v[50:65], v[238:241], v[218:221], v[50:65]
	v_cvt_pk_bf16_f32 v174, v114, s0
	ds_write_b16 v213, v174 offset:43008
	v_cvt_pk_bf16_f32 v175, v115, s0
	ds_write_b16 v213, v175 offset:43264
	v_cvt_pk_bf16_f32 v176, v116, s0
	ds_write_b16 v213, v176 offset:43520
	v_cvt_pk_bf16_f32 v177, v117, s0
	ds_write_b16 v213, v177 offset:43776
	v_add_u32_e32 v195, s60, v194
	s_waitcnt lgkmcnt(11)
; __device__ __forceinline__ int opaque_tid() { int t = threadIdx.x; asm volatile("" : "+v"(t)); return t; }
; #define BAR_LDS() do { asm volatile("s_waitcnt lgkmcnt(0)" ::: "memory"); __builtin_amdgcn_s_barrier(); asm volatile("" ::: "memory"); } while (0)
; #define MFMA32(a, b, c) __builtin_amdgcn_mfma_f32_32x32x16_bf16((a), (b), (c), 0, 0, 0)
; template <int VAR> __device__ __forceinline__ void dn_scan3(LAS unsigned char* lds, const bf16_t* P, const float* AB, const bf16_t* TP, bf16_t* OB) {
;     ...
;             if (w < 3) {
;                 const int qh = w >= 1 ? 1 : 0, khh = w == 2 ? 1 : 0, ti = qh, tj = khh;
;                 u32x4 q8[8], k8[8]; float gcp;
;                 {
;                     int rb; bool f_; dn_step_rb(0, dir, b, rb, f_);
;                     const int lane = opaque_tid() & 63, r0 = lane >> 4, c8 = 8 * (lane & 15);
; #pragma unroll
;                     for (int v = 0; v < 8; ++v) { const int ipq = 32 * qh + r0 + 4 * v, ipk = 32 * khh + r0 + 4 * v, iq = dir ? 63 - ipq : ipq, ik = dir ? 63 - ipk : ipk;
;                         q8[v] = *(const u32x4*)(P + (size_t)(rb * 64 + iq) * 4096 + kh * 128 + c8); k8[v] = *(const u32x4*)(P + (size_t)(rb * 64 + ik) * 4096 + 1024 + kh * 128 + c8); }
;                     const int tl = dir ? 63 - lane : lane; gcp = AB[(size_t)(rb * 64 + tl) * 64 + dir * 16 + vh];
;     ...
;                 for (int ks = 0; ks < 4; ++ks) {
; #pragma unroll
;                     for (int kt = 0; kt < 4; ++kt) S[kt] = MFMA32(frag_tr(Kb, 136, 32 * kt, ks, lane), VNp[ks], S[kt]);
;                 }
;                 }
;                 BAR_LDS();
;             }
	global_atomic_pk_add_bf16 v195, v154, s[42:43]
	v_add_u32_e32 v200, s61, v194
	s_waitcnt lgkmcnt(10)
	global_atomic_pk_add_bf16 v200, v155, s[42:43]
	v_mfma_f32_32x32x16_bf16 v[34:49], v[158:161], v[218:221], v[34:49]
	v_cvt_pk_bf16_f32 v174, v118, s0
	ds_write_b16 v213, v174 offset:45056
	v_cvt_pk_bf16_f32 v175, v119, s0
	ds_write_b16 v213, v175 offset:45312
	v_cvt_pk_bf16_f32 v176, v120, s0
	ds_write_b16 v213, v176 offset:45568
	v_cvt_pk_bf16_f32 v177, v121, s0
	ds_write_b16 v213, v177 offset:45824
	v_add_u32_e32 v195, s62, v195
	s_waitcnt lgkmcnt(13)
	global_atomic_pk_add_bf16 v195, v156, s[42:43]
	v_add_u32_e32 v200, s62, v200
	s_waitcnt lgkmcnt(12)
	global_atomic_pk_add_bf16 v200, v157, s[42:43]
	v_mfma_f32_32x32x16_bf16 v[18:33], v[226:229], v[218:221], v[18:33]
	v_cvt_pk_bf16_f32 v174, v122, s0
	ds_write_b16 v213, v174 offset:47104
	v_cvt_pk_bf16_f32 v175, v123, s0
	ds_write_b16 v213, v175 offset:47360
	v_cvt_pk_bf16_f32 v176, v124, s0
	ds_write_b16 v213, v176 offset:47616
	v_cvt_pk_bf16_f32 v177, v125, s0
	ds_write_b16 v213, v177 offset:47872
	v_add_u32_e32 v195, s62, v195
	global_atomic_pk_add_bf16 v195, v162, s[42:43]
	v_add_u32_e32 v200, s62, v200
	s_waitcnt lgkmcnt(14)
	global_atomic_pk_add_bf16 v200, v163, s[42:43]
	v_mfma_f32_32x32x16_bf16 v[2:17], v[130:133], v[218:221], v[2:17]
	v_cvt_pk_bf16_f32 v174, v126, s0
	ds_write_b16 v213, v174 offset:49152
	v_cvt_pk_bf16_f32 v175, v127, s0
	ds_write_b16 v213, v175 offset:49408
	v_cvt_pk_bf16_f32 v176, v128, s0
	ds_write_b16 v213, v176 offset:49664
	v_cvt_pk_bf16_f32 v177, v129, s0
	ds_write_b16 v213, v177 offset:49920
	v_add_u32_e32 v195, s62, v195
	global_atomic_pk_add_bf16 v195, v164, s[42:43]
	v_add_u32_e32 v200, s62, v200
	global_atomic_pk_add_bf16 v200, v165, s[42:43]
	v_mfma_f32_32x32x16_bf16 v[50:65], v[138:141], v[230:233], v[50:65]
	ds_read_b32 v130, v179 offset:43008
	ds_read_b32 v131, v179 offset:44032
	ds_read_b32 v132, v179 offset:45056
	ds_read_b32 v133, v179 offset:46080
	ds_read_b32 v138, v179 offset:47104
	ds_read_b32 v139, v179 offset:48128
	ds_read_b32 v140, v179 offset:49152
	ds_read_b32 v141, v179 offset:50176
	v_mfma_f32_32x32x16_bf16 v[34:49], v[142:145], v[230:233], v[34:49]
	v_add_u32_e32 v195, s62, v195
	s_waitcnt lgkmcnt(7)
	global_atomic_pk_add_bf16 v195, v130, s[42:43]
	v_add_u32_e32 v200, s62, v200
	s_waitcnt lgkmcnt(6)
	global_atomic_pk_add_bf16 v200, v131, s[42:43]
	v_mfma_f32_32x32x16_bf16 v[18:33], v[146:149], v[230:233], v[18:33]
	v_add_u32_e32 v195, s62, v195
	s_waitcnt lgkmcnt(5)
	global_atomic_pk_add_bf16 v195, v132, s[42:43]
	v_add_u32_e32 v200, s62, v200
	s_waitcnt lgkmcnt(4)
	global_atomic_pk_add_bf16 v200, v133, s[42:43]
	v_mfma_f32_32x32x16_bf16 v[2:17], v[150:153], v[230:233], v[2:17]
	v_add_u32_e32 v195, s62, v195
	s_waitcnt lgkmcnt(3)
	global_atomic_pk_add_bf16 v195, v138, s[42:43]
	v_add_u32_e32 v200, s62, v200
	s_waitcnt lgkmcnt(2)
	global_atomic_pk_add_bf16 v200, v139, s[42:43]
	v_add_u32_e32 v195, s62, v195
	s_waitcnt lgkmcnt(1)
	global_atomic_pk_add_bf16 v195, v140, s[42:43]
	v_add_u32_e32 v200, s62, v200
	s_waitcnt lgkmcnt(0)
	global_atomic_pk_add_bf16 v200, v141, s[42:43]
	s_waitcnt lgkmcnt(0)
	s_barrier
	s_add_i32 s40, s40, 1
	s_cmpk_lg_i32 s40, 0x104
	s_cbranch_scc1 .LBB0_377
	s_mov_b64 s[40:41], 0
.LBB0_379:
	s_and_b64 vcc, exec, s[40:41]
	s_cbranch_vccz .LBB0_374
	s_ashr_i32 s56, s54, 5
	s_bfe_u32 s57, s54, 0x40001
	s_and_b32 s58, s54, 1
	s_bfe_i32 s42, s54, 0x10000
	s_cmp_eq_u32 s58, 0
	s_cselect_b64 s[40:41], -1, 0
	s_lshl_b32 s55, s56, 2
	s_and_b32 s42, s42, 3
	s_addk_i32 s55, 0x200
	s_or_b32 s59, s55, s42
	s_andn2_b64 vcc, exec, s[10:11]
	s_mov_b64 s[42:43], -1
	s_cbranch_vccnz .LBB0_448
	v_mov_b32_e32 v8, v188
	s_lshl_b32 s44, s59, 6
	v_bfe_u32 v10, v8, 4, 2
	v_or_b32_e32 v12, s52, v10
	v_bitop3_b32 v5, v10, 63, s52 bitop3:0x36
	v_cndmask_b32_e64 v6, v5, v12, s[40:41]
	v_or_b32_e32 v11, s19, v10
	s_lshl_b32 s42, s57, 7
	v_bitop3_b32 v4, v10, 63, s19 bitop3:0x36
	v_or_b32_e32 v6, s44, v6
	s_and_b32 s80, s42, 0x700
	v_cndmask_b32_e64 v4, v4, v11, s[40:41]
	v_ashrrev_i32_e32 v7, 31, v6
	s_add_u32 s42, s96, s80
	v_lshlrev_b32_e32 v0, 4, v8
	v_or_b32_e32 v4, s44, v4
	v_lshlrev_b64 v[6:7], 13, v[6:7]
	s_addc_u32 s43, s97, 0
	v_and_b32_e32 v0, 0xf0, v0
	v_ashrrev_i32_e32 v5, 31, v4
	v_lshl_add_u64 v[6:7], s[96:97], 0, v[6:7]
	v_lshl_add_u64 v[2:3], s[42:43], 0, v[0:1]
	v_lshlrev_b64 v[4:5], 13, v[4:5]
	v_lshl_add_u64 v[6:7], v[6:7], 0, s[80:81]
	v_lshl_add_u64 v[4:5], v[2:3], 0, v[4:5]
	v_lshl_add_u64 v[6:7], v[6:7], 0, v[0:1]
	global_load_dwordx4 v[22:25], v[4:5], off
	global_load_dwordx4 v[18:21], v[6:7], off offset:2048
	v_or_b32_e32 v4, 4, v11
	v_bitop3_b32 v6, v10, 59, s19 bitop3:0x36
	v_or_b32_e32 v5, 4, v12
	v_cndmask_b32_e64 v4, v6, v4, s[40:41]
	v_bitop3_b32 v6, v10, 59, s52 bitop3:0x36
	v_cndmask_b32_e64 v6, v6, v5, s[40:41]
	v_or_b32_e32 v6, s44, v6
	v_ashrrev_i32_e32 v7, 31, v6
	v_or_b32_e32 v4, s44, v4
	v_lshlrev_b64 v[6:7], 13, v[6:7]
	v_ashrrev_i32_e32 v5, 31, v4
	v_lshl_add_u64 v[6:7], s[96:97], 0, v[6:7]
	v_lshlrev_b64 v[4:5], 13, v[4:5]
	v_lshl_add_u64 v[6:7], v[6:7], 0, s[80:81]
	v_lshl_add_u64 v[4:5], v[2:3], 0, v[4:5]
	v_lshl_add_u64 v[6:7], v[6:7], 0, v[0:1]
	global_load_dwordx4 v[26:29], v[4:5], off
	global_load_dwordx4 v[30:33], v[6:7], off offset:2048
	v_or_b32_e32 v4, 8, v11
	v_bitop3_b32 v6, v10, 55, s19 bitop3:0x36
	v_or_b32_e32 v5, 8, v12
	v_cndmask_b32_e64 v4, v6, v4, s[40:41]
	v_bitop3_b32 v6, v10, 55, s52 bitop3:0x36
	v_cndmask_b32_e64 v6, v6, v5, s[40:41]
	v_or_b32_e32 v6, s44, v6
	v_ashrrev_i32_e32 v7, 31, v6
	v_or_b32_e32 v4, s44, v4
	v_lshlrev_b64 v[6:7], 13, v[6:7]
	v_ashrrev_i32_e32 v5, 31, v4
; __device__ __forceinline__ int opaque_tid() { int t = threadIdx.x; asm volatile("" : "+v"(t)); return t; }
; template <int VAR> __device__ __forceinline__ void dn_scan3(LAS unsigned char* lds, const bf16_t* P, const float* AB, const bf16_t* TP, bf16_t* OB) {
;     ...
;                     int rb; bool f_; dn_step_rb(0, dir, b, rb, f_);
;                     const int lane = opaque_tid() & 63, r0 = lane >> 4, c8 = 8 * (lane & 15);
; #pragma unroll
;                     for (int v = 0; v < 8; ++v) { const int ipq = 32 * qh + r0 + 4 * v, ipk = 32 * khh + r0 + 4 * v, iq = dir ? 63 - ipq : ipq, ik = dir ? 63 - ipk : ipk;
;                         q8[v] = *(const u32x4*)(P + (size_t)(rb * 64 + iq) * 4096 + kh * 128 + c8); k8[v] = *(const u32x4*)(P + (size_t)(rb * 64 + ik) * 4096 + 1024 + kh * 128 + c8); }
;                     const int tl = dir ? 63 - lane : lane; gcp = AB[(size_t)(rb * 64 + tl) * 64 + dir * 16 + vh];
;     ...
;                         for (int v = 0; v < 8; ++v) { const int ipq = 32 * qh + r0 + 4 * v, ipk = 32 * khh + r0 + 4 * v, iq = dir ? 63 - ipq : ipq, ik = dir ? 63 - ipk : ipk;
;                             q8[v] = *(const u32x4*)(P + (size_t)(rb * 64 + iq) * 4096 + kh * 128 + c8); k8[v] = *(const u32x4*)(P + (size_t)(rb * 64 + ik) * 4096 + 1024 + kh * 128 + c8); }
	v_lshl_add_u64 v[6:7], s[96:97], 0, v[6:7]
	v_lshlrev_b64 v[4:5], 13, v[4:5]
	v_lshl_add_u64 v[6:7], v[6:7], 0, s[80:81]
	v_lshl_add_u64 v[4:5], v[2:3], 0, v[4:5]
	v_lshl_add_u64 v[6:7], v[6:7], 0, v[0:1]
	global_load_dwordx4 v[34:37], v[4:5], off
	global_load_dwordx4 v[38:41], v[6:7], off offset:2048
	v_or_b32_e32 v4, 12, v11
	v_bitop3_b32 v6, v10, 51, s19 bitop3:0x36
	v_or_b32_e32 v5, 12, v12
	v_cndmask_b32_e64 v4, v6, v4, s[40:41]
	v_bitop3_b32 v6, v10, 51, s52 bitop3:0x36
	v_cndmask_b32_e64 v6, v6, v5, s[40:41]
	v_or_b32_e32 v6, s44, v6
	v_ashrrev_i32_e32 v7, 31, v6
	v_or_b32_e32 v4, s44, v4
	v_lshlrev_b64 v[6:7], 13, v[6:7]
	v_ashrrev_i32_e32 v5, 31, v4
	v_lshl_add_u64 v[6:7], s[96:97], 0, v[6:7]
	v_lshlrev_b64 v[4:5], 13, v[4:5]
	v_lshl_add_u64 v[6:7], v[6:7], 0, s[80:81]
	v_lshl_add_u64 v[4:5], v[2:3], 0, v[4:5]
	v_lshl_add_u64 v[6:7], v[6:7], 0, v[0:1]
	global_load_dwordx4 v[42:45], v[4:5], off
	global_load_dwordx4 v[46:49], v[6:7], off offset:2048
	v_or_b32_e32 v4, 16, v11
	v_bitop3_b32 v6, v10, 47, s19 bitop3:0x36
	v_or_b32_e32 v5, 16, v12
	v_cndmask_b32_e64 v4, v6, v4, s[40:41]
	v_bitop3_b32 v6, v10, 47, s52 bitop3:0x36
	v_cndmask_b32_e64 v6, v6, v5, s[40:41]
	v_or_b32_e32 v6, s44, v6
	v_ashrrev_i32_e32 v7, 31, v6
	v_or_b32_e32 v4, s44, v4
	v_lshlrev_b64 v[6:7], 13, v[6:7]
	v_ashrrev_i32_e32 v5, 31, v4
	v_lshl_add_u64 v[6:7], s[96:97], 0, v[6:7]
	v_lshlrev_b64 v[4:5], 13, v[4:5]
	v_lshl_add_u64 v[6:7], v[6:7], 0, s[80:81]
	v_lshl_add_u64 v[4:5], v[2:3], 0, v[4:5]
	v_lshl_add_u64 v[6:7], v[6:7], 0, v[0:1]
	global_load_dwordx4 v[54:57], v[4:5], off
	global_load_dwordx4 v[50:53], v[6:7], off offset:2048
	v_or_b32_e32 v4, 20, v11
	v_bitop3_b32 v6, v10, 43, s19 bitop3:0x36
	v_or_b32_e32 v5, 20, v12
	v_cndmask_b32_e64 v4, v6, v4, s[40:41]
	v_bitop3_b32 v6, v10, 43, s52 bitop3:0x36
	v_cndmask_b32_e64 v6, v6, v5, s[40:41]
	v_or_b32_e32 v6, s44, v6
	v_ashrrev_i32_e32 v7, 31, v6
	v_or_b32_e32 v4, s44, v4
	v_lshlrev_b64 v[6:7], 13, v[6:7]
	v_ashrrev_i32_e32 v5, 31, v4
	v_lshl_add_u64 v[6:7], s[96:97], 0, v[6:7]
	v_lshlrev_b64 v[4:5], 13, v[4:5]
	v_lshl_add_u64 v[6:7], v[6:7], 0, s[80:81]
	v_lshl_add_u64 v[4:5], v[2:3], 0, v[4:5]
	v_lshl_add_u64 v[6:7], v[6:7], 0, v[0:1]
	global_load_dwordx4 v[62:65], v[4:5], off
	global_load_dwordx4 v[58:61], v[6:7], off offset:2048
	v_or_b32_e32 v4, 24, v11
	v_bitop3_b32 v6, v10, 39, s19 bitop3:0x36
	v_or_b32_e32 v5, 24, v12
	v_cndmask_b32_e64 v4, v6, v4, s[40:41]
	v_bitop3_b32 v6, v10, 39, s52 bitop3:0x36
	v_cndmask_b32_e64 v6, v6, v5, s[40:41]
	v_or_b32_e32 v6, s44, v6
	v_ashrrev_i32_e32 v7, 31, v6
	v_or_b32_e32 v4, s44, v4
	v_lshlrev_b64 v[6:7], 13, v[6:7]
	v_ashrrev_i32_e32 v5, 31, v4
	v_lshl_add_u64 v[6:7], s[96:97], 0, v[6:7]
	v_lshlrev_b64 v[4:5], 13, v[4:5]
	v_lshl_add_u64 v[6:7], v[6:7], 0, s[80:81]
	v_lshl_add_u64 v[4:5], v[2:3], 0, v[4:5]
	v_lshl_add_u64 v[6:7], v[6:7], 0, v[0:1]
	global_load_dwordx4 v[70:73], v[4:5], off
	global_load_dwordx4 v[66:69], v[6:7], off offset:2048
	v_or_b32_e32 v4, 28, v11
	v_bitop3_b32 v6, v10, 35, s19 bitop3:0x36
	v_cndmask_b32_e64 v4, v6, v4, s[40:41]
	v_or_b32_e32 v5, 28, v12
	v_bitop3_b32 v6, v10, 35, s52 bitop3:0x36
	v_or_b32_e32 v4, s44, v4
	v_cndmask_b32_e64 v6, v6, v5, s[40:41]
	v_ashrrev_i32_e32 v5, 31, v4
	v_lshlrev_b64 v[4:5], 13, v[4:5]
	v_lshl_add_u64 v[2:3], v[2:3], 0, v[4:5]
	v_or_b32_e32 v4, s44, v6
	v_ashrrev_i32_e32 v5, 31, v4
	v_lshlrev_b64 v[4:5], 13, v[4:5]
	v_lshl_add_u64 v[4:5], s[96:97], 0, v[4:5]
	v_lshl_add_u64 v[4:5], v[4:5], 0, s[80:81]
	v_and_b32_e32 v9, 63, v8
	v_lshl_add_u64 v[4:5], v[4:5], 0, v[0:1]
	v_bitop3_b32 v0, v8, 63, v8 bitop3:0xc
	v_cndmask_b32_e64 v0, v0, v9, s[40:41]
	global_load_dwordx4 v[78:81], v[2:3], off
	global_load_dwordx4 v[74:77], v[4:5], off offset:2048
	v_or_b32_e32 v2, s44, v0
	v_ashrrev_i32_e32 v3, 31, v2
	v_readlane_b32 s48, v251, 12
	v_lshlrev_b64 v[2:3], 8, v[2:3]
	v_readlane_b32 s49, v251, 13
	s_lshl_b32 s80, s58, 6
	s_lshl_b32 s44, s57, 2
	v_lshl_add_u64 v[2:3], s[48:49], 0, v[2:3]
	v_lshl_add_u64 v[2:3], v[2:3], 0, s[80:81]
	s_mov_b32 s45, s81
	v_lshl_add_u64 v[2:3], v[2:3], 0, s[44:45]
	global_load_dword v82, v[2:3], off
	s_add_u32 s45, s48, s80
	s_addc_u32 s48, s49, 0
	s_add_u32 s44, s45, s44
	s_addc_u32 s45, s48, 0
	s_lshl_b32 s60, s56, 8
	s_mov_b32 s61, 0
	s_mov_b32 s62, 0
	v_bfe_u32 v156, v188, 4, 2
	v_lshlrev_b32_e32 v157, 4, v188
	v_and_b32_e32 v157, 0xf0, v157
	v_mov_b32_e32 v158, v156
	v_or_b32_e32 v159, s19, v158
	v_xor_b32_e32 v160, 63, v159
	v_cndmask_b32_e64 v159, v160, v159, s[40:41]
	v_lshl_add_u32 v140, v159, 13, v157
	v_or_b32_e32 v159, s52, v158
	v_xor_b32_e32 v160, 63, v159
	v_cndmask_b32_e64 v159, v160, v159, s[40:41]
	v_lshl_add_u32 v141, v159, 13, v157
	v_or_b32_e32 v158, 4, v156
	v_or_b32_e32 v159, s19, v158
	v_xor_b32_e32 v160, 63, v159
	v_cndmask_b32_e64 v159, v160, v159, s[40:41]
	v_lshl_add_u32 v142, v159, 13, v157
	v_or_b32_e32 v159, s52, v158
	v_xor_b32_e32 v160, 63, v159
	v_cndmask_b32_e64 v159, v160, v159, s[40:41]
	v_lshl_add_u32 v143, v159, 13, v157
	v_or_b32_e32 v158, 8, v156
	v_or_b32_e32 v159, s19, v158
	v_xor_b32_e32 v160, 63, v159
	v_cndmask_b32_e64 v159, v160, v159, s[40:41]
	v_lshl_add_u32 v144, v159, 13, v157
	v_or_b32_e32 v159, s52, v158
	v_xor_b32_e32 v160, 63, v159
	v_cndmask_b32_e64 v159, v160, v159, s[40:41]
	v_lshl_add_u32 v145, v159, 13, v157
	v_or_b32_e32 v158, 12, v156
	v_or_b32_e32 v159, s19, v158
	v_xor_b32_e32 v160, 63, v159
	v_cndmask_b32_e64 v159, v160, v159, s[40:41]
	v_lshl_add_u32 v146, v159, 13, v157
	v_or_b32_e32 v159, s52, v158
	v_xor_b32_e32 v160, 63, v159
	v_cndmask_b32_e64 v159, v160, v159, s[40:41]
	v_lshl_add_u32 v147, v159, 13, v157
	v_or_b32_e32 v158, 16, v156
	v_or_b32_e32 v159, s19, v158
	v_xor_b32_e32 v160, 63, v159
	v_cndmask_b32_e64 v159, v160, v159, s[40:41]
	v_lshl_add_u32 v148, v159, 13, v157
	v_or_b32_e32 v159, s52, v158
	v_xor_b32_e32 v160, 63, v159
	v_cndmask_b32_e64 v159, v160, v159, s[40:41]
	v_lshl_add_u32 v149, v159, 13, v157
	v_or_b32_e32 v158, 20, v156
	v_or_b32_e32 v159, s19, v158
	v_xor_b32_e32 v160, 63, v159
	v_cndmask_b32_e64 v159, v160, v159, s[40:41]
	v_lshl_add_u32 v150, v159, 13, v157
	v_or_b32_e32 v159, s52, v158
	v_xor_b32_e32 v160, 63, v159
	v_cndmask_b32_e64 v159, v160, v159, s[40:41]
	v_lshl_add_u32 v151, v159, 13, v157
	v_or_b32_e32 v158, 24, v156
	v_or_b32_e32 v159, s19, v158
	v_xor_b32_e32 v160, 63, v159
	v_cndmask_b32_e64 v159, v160, v159, s[40:41]
	v_lshl_add_u32 v152, v159, 13, v157
	v_or_b32_e32 v159, s52, v158
	v_xor_b32_e32 v160, 63, v159
	v_cndmask_b32_e64 v159, v160, v159, s[40:41]
	v_lshl_add_u32 v153, v159, 13, v157
	v_or_b32_e32 v158, 28, v156
	v_or_b32_e32 v159, s19, v158
	v_xor_b32_e32 v160, 63, v159
	v_cndmask_b32_e64 v159, v160, v159, s[40:41]
	v_lshl_add_u32 v154, v159, 13, v157
	v_or_b32_e32 v159, s52, v158
	v_xor_b32_e32 v160, 63, v159
	v_cndmask_b32_e64 v159, v160, v159, s[40:41]
	v_lshl_add_u32 v155, v159, 13, v157
	s_branch .LBB0_383

; __device__ __forceinline__ int opaque_tid() { int t = threadIdx.x; asm volatile("" : "+v"(t)); return t; }
; template <int VAR> __device__ __forceinline__ void dn_scan3(LAS unsigned char* lds, const bf16_t* P, const float* AB, const bf16_t* TP, bf16_t* OB) {
;     ...
;                 for (int j = 0; j < 260; ++j) {
;                     const int lane = opaque_tid() & 63, r = lane & 31, h = lane >> 5, r0 = lane >> 4, c8 = 8 * (lane & 15);
;                     LAS unsigned char* base = lds + (j & 1) * DN_DIR;
;                     LAS bf16_t* Kb = (LAS bf16_t*)(base + DN_KB); LAS bf16_t* Qb = (LAS bf16_t*)(base + DN_QB); LAS bf16_t* Ab = (LAS bf16_t*)(base + DN_AB);
;                     LAS float* hgc = (LAS float*)(lds + DN3_HGC + w * 256);
; #pragma unroll
;                     for (int v = 0; v < 8; ++v) { *(LAS u32x4*)(Qb + (32 * qh + r0 + 4 * v) * 136 + c8) = q8[v]; *(LAS u32x4*)(Kb + (32 * khh + r0 + 4 * v) * 136 + c8) = k8[v]; }
;                     hgc[lane] = gcp;
;                     asm volatile("s_waitcnt lgkmcnt(0)" ::: "memory");
;                     if (j + 1 < 260) {
;                         int rb; bool f_; dn_step_rb(j + 1, dir, b, rb, f_);
; #pragma unroll
;                         for (int v = 0; v < 8; ++v) { const int ipq = 32 * qh + r0 + 4 * v, ipk = 32 * khh + r0 + 4 * v, iq = dir ? 63 - ipq : ipq, ik = dir ? 63 - ipk : ipk;
;                             q8[v] = *(const u32x4*)(P + (size_t)(rb * 64 + iq) * 4096 + kh * 128 + c8); k8[v] = *(const u32x4*)(P + (size_t)(rb * 64 + ik) * 4096 + 1024 + kh * 128 + c8); }
;                         const int tl = dir ? 63 - lane : lane; gcp = AB[(size_t)(rb * 64 + tl) * 64 + dir * 16 + vh];
;                     }
;                     __builtin_amdgcn_sched_barrier(0);
;                     {
;                         f32x16 qk;
; #pragma unroll
;                         for (int x = 0; x < 16; ++x) qk[x] = 0.f;
; #pragma unroll
;                         for (int ks = 0; ks < 8; ++ks) qk = MFMA32(frag_nat(Qb, 136, 32 * ti + r, ks, h), frag_nat(Kb, 136, 32 * tj + r, ks, h), qk);
;                         const int jj = 32 * tj + r; const float gj = hgc[jj];
; #pragma unroll
;                         for (int x = 0; x < 16; ++x) { const int i = 32 * ti + crow(x, h);
;                             Ab[i * 72 + jj] = f2bf((i >= jj) ? qk[x] * __expf(hgc[i] - gj) : 0.f); }
.LBB0_383:
	s_bitcmp1_b32 s62, 0
	s_mov_b32 s49, s62
	s_cselect_b32 s48, 0x11600, 0
	s_add_i32 s48, s48, 0
	s_add_i32 s62, s62, 1
	s_add_i32 s63, s49, -3
	s_cmp_lt_u32 s49, 3
	s_cselect_b32 s49, 2, 0x102
	s_cselect_b32 s63, s62, s63
	s_cselect_b32 s66, s55, s60
	s_add_i32 s49, s49, s61
	v_mov_b32_e32 v8, v188
	s_and_b64 s[64:65], s[40:41], exec
	s_cselect_b32 s49, s63, s49
	v_bfe_u32 v10, v8, 4, 2
	v_lshlrev_b32_e32 v0, 4, v8
	v_or_b32_e32 v12, s52, v10
	s_add_i32 s49, s49, s66
	v_bitop3_b32 v5, v10, 63, s52 bitop3:0x36
	v_or_b32_e32 v11, s19, v10
	v_and_b32_e32 v0, 0xf0, v0
	s_lshl_b32 s49, s49, 6
	v_bitop3_b32 v4, v10, 63, s19 bitop3:0x36
	v_cndmask_b32_e64 v6, v5, v12, s[40:41]
	v_add_u32_e32 v2, s48, v0
	v_cndmask_b32_e64 v4, v4, v11, s[40:41]
	v_or_b32_e32 v6, s49, v6
	v_and_b32_e32 v9, 63, v8
	v_mad_u32_u24 v3, v11, s38, v2
	v_mad_u32_u24 v2, v12, s38, v2
	v_or_b32_e32 v4, s49, v4
	v_ashrrev_i32_e32 v7, 31, v6
	s_waitcnt vmcnt(16)
	ds_write_b128 v3, v[22:25] offset:17408
	s_waitcnt vmcnt(15)
	ds_write_b128 v2, v[18:21]
	s_waitcnt vmcnt(14)
	ds_write_b128 v3, v[26:29] offset:18496
	s_waitcnt vmcnt(13)
	ds_write_b128 v2, v[30:33] offset:1088
	s_waitcnt vmcnt(12)
	ds_write_b128 v3, v[34:37] offset:19584
	s_waitcnt vmcnt(11)
	ds_write_b128 v2, v[38:41] offset:2176
	s_waitcnt vmcnt(10)
	ds_write_b128 v3, v[42:45] offset:20672
	s_waitcnt vmcnt(9)
	ds_write_b128 v2, v[46:49] offset:3264
	s_waitcnt vmcnt(8)
	ds_write_b128 v3, v[54:57] offset:21760
	s_waitcnt vmcnt(7)
	ds_write_b128 v2, v[50:53] offset:4352
	s_waitcnt vmcnt(6)
	ds_write_b128 v3, v[62:65] offset:22848
	s_waitcnt vmcnt(5)
	ds_write_b128 v2, v[58:61] offset:5440
	s_waitcnt vmcnt(4)
	ds_write_b128 v3, v[70:73] offset:23936
	s_waitcnt vmcnt(3)
	ds_write_b128 v2, v[66:69] offset:6528
	s_waitcnt vmcnt(2)
	ds_write_b128 v3, v[78:81] offset:25024
	s_waitcnt vmcnt(1)
	ds_write_b128 v2, v[74:77] offset:7616
	v_lshl_add_u32 v2, v9, 2, s53
	v_ashrrev_i32_e32 v5, 31, v4
	v_lshlrev_b64 v[6:7], 13, v[6:7]
	s_waitcnt vmcnt(0)
	ds_write_b32 v2, v82
	s_waitcnt lgkmcnt(0)
	s_lshl_b32 s64, s49, 13
	s_add_u32 s64, s42, s64
	s_addc_u32 s65, s43, 0
	global_load_dwordx4 v[22:25], v140, s[64:65]
	global_load_dwordx4 v[18:21], v141, s[64:65] offset:2048
	global_load_dwordx4 v[26:29], v142, s[64:65]
	global_load_dwordx4 v[30:33], v143, s[64:65] offset:2048
	global_load_dwordx4 v[34:37], v144, s[64:65]
	global_load_dwordx4 v[38:41], v145, s[64:65] offset:2048
	global_load_dwordx4 v[42:45], v146, s[64:65]
	global_load_dwordx4 v[46:49], v147, s[64:65] offset:2048
	global_load_dwordx4 v[54:57], v148, s[64:65]
	global_load_dwordx4 v[50:53], v149, s[64:65] offset:2048
	global_load_dwordx4 v[62:65], v150, s[64:65]
	global_load_dwordx4 v[58:61], v151, s[64:65] offset:2048
	global_load_dwordx4 v[70:73], v152, s[64:65]
	global_load_dwordx4 v[66:69], v153, s[64:65] offset:2048
	global_load_dwordx4 v[78:81], v154, s[64:65]
	global_load_dwordx4 v[74:77], v155, s[64:65] offset:2048
	v_bitop3_b32 v0, v8, 63, v8 bitop3:0xc
	v_cndmask_b32_e64 v0, v0, v9, s[40:41]
	v_or_b32_e32 v2, s49, v0
	v_ashrrev_i32_e32 v3, 31, v2
	v_lshlrev_b64 v[2:3], 8, v[2:3]
	v_lshl_add_u64 v[2:3], s[44:45], 0, v[2:3]
	global_load_dword v82, v[2:3], off
	v_and_b32_e32 v0, 31, v8
	v_bfe_u32 v84, v8, 5, 1
	v_or_b32_e32 v2, s19, v0
	v_mul_u32_u24_e32 v2, 0x110, v2
	v_lshlrev_b32_e32 v6, 4, v84
	v_add3_u32 v83, s48, v2, v6
	ds_read_b128 v[2:5], v83 offset:17408
	v_or_b32_e32 v0, s52, v0
	v_mov_b32_e32 v7, s48
	v_mad_u32_u24 v86, v0, s38, v7
	v_add_u32_e32 v85, v86, v6
	ds_read_b128 v[6:9], v85
	ds_read_b128 v[88:91], v83 offset:17440
	ds_read_b128 v[92:95], v85 offset:32
	v_mov_b32_e32 v87, 0
	s_waitcnt lgkmcnt(2)
	v_mfma_f32_32x32x16_bf16 v[2:17], v[2:5], v[6:9], 0
	s_waitcnt lgkmcnt(0)
	v_mfma_f32_32x32x16_bf16 v[2:17], v[88:91], v[92:95], v[2:17]
	ds_read_b128 v[88:91], v83 offset:17472
	ds_read_b128 v[92:95], v85 offset:64
	s_waitcnt lgkmcnt(0)
	v_mfma_f32_32x32x16_bf16 v[2:17], v[88:91], v[92:95], v[2:17]
	ds_read_b128 v[88:91], v83 offset:17504
	ds_read_b128 v[92:95], v85 offset:96
	s_waitcnt lgkmcnt(0)
	v_mfma_f32_32x32x16_bf16 v[2:17], v[88:91], v[92:95], v[2:17]
	ds_read_b128 v[88:91], v83 offset:17536
	ds_read_b128 v[92:95], v85 offset:128
	s_waitcnt lgkmcnt(0)
	v_mfma_f32_32x32x16_bf16 v[2:17], v[88:91], v[92:95], v[2:17]
	ds_read_b128 v[88:91], v83 offset:17568
	ds_read_b128 v[92:95], v85 offset:160
	s_waitcnt lgkmcnt(0)
	v_mfma_f32_32x32x16_bf16 v[2:17], v[88:91], v[92:95], v[2:17]
	ds_read_b128 v[88:91], v83 offset:17600
	ds_read_b128 v[92:95], v85 offset:192
	s_waitcnt lgkmcnt(0)
	v_mfma_f32_32x32x16_bf16 v[2:17], v[88:91], v[92:95], v[2:17]
	ds_read_b128 v[88:91], v83 offset:17632
	ds_read_b128 v[92:95], v85 offset:224
	v_lshl_add_u32 v83, v0, 2, s53
	ds_read_b32 v83, v83
	v_lshl_or_b32 v85, v84, 2, s19
	v_cmp_ge_u32_e32 vcc, v85, v0
	v_lshl_add_u32 v84, v85, 2, s53
	s_waitcnt lgkmcnt(1)
	v_mfma_f32_32x32x16_bf16 v[2:17], v[88:91], v[92:95], v[2:17]
	v_mov_b32_e32 v88, 0
	s_and_saveexec_b64 s[48:49], vcc
	s_cbranch_execz .LBB0_385
	ds_read_b32 v88, v84
	s_waitcnt lgkmcnt(0)
	v_sub_f32_e32 v88, v88, v83
	v_mul_f32_e32 v88, 0x3fb8aa3b, v88
	v_exp_f32_e32 v88, v88
	s_nop 3
	v_mul_f32_e32 v2, v2, v88
	v_cvt_pk_bf16_f32 v88, v2, s0
